# scan phase: 64 serialized load-wait-store steps replaced by two batches of 32 prefetched steps (saddr global loads, wave-uniform chunk index)
# speedup vs baseline: 1.0126x; 1.0126x over previous
; __device__ __forceinline__ unsigned cvt_pk_bf16(float lo, float hi) { unsigned r; asm volatile("v_cvt_pk_bf16_f32 %0, %1, %2" : "=v"(r) : "v"(lo), "v"(hi)); return r; }
; __device__ __forceinline__ int otid() { int t = threadIdx.x; asm volatile("" : "+v"(t)); return t; }
; __device__ __forceinline__ void scan_phase(const Args& a) {
;     const bf16_t* kvt = (const bf16_t*)(a.ws + WS_KVT); const float* dec = (const float*)(a.ws + WS_DEC); bf16_t* st = (bf16_t*)(a.ws + WS_ST);
;     const int tid = otid();
;     for (int g = blockIdx.x * NTHR + tid; g < 32 * 4096; g += gridDim.x * NTHR) {
;         const int seq = g >> 12, e2 = g & 4095, v = e2 >> 5, k2 = (e2 & 31) * 2, dir = seq & 1; float s0 = 0.f, s1 = 0.f;
; #pragma unroll 8
;         for (int step = 0; step < 64; ++step) { const int c = dir ? 63 - step : step; const size_t idx = (size_t)seq * 64 + c;
;             const unsigned kw = *(const unsigned*)(kvt + idx * 8192 + v * 64 + k2); const f32x2 kv = (f32x2){bflo(kw), bfhi(kw)}; const f32x2 d = *(const f32x2*)(dec + idx * 64 + k2);
;             *(unsigned*)(st + idx * 8192 + v * 64 + k2) = cvt_pk_bf16(s0, s1);
;             s0 = d.x * s0 + kv.x; s1 = d.y * s1 + kv.y; }
;     }
.LBB0_150:
	v_lshlrev_b32_e32 v0, 2, v12
	v_and_b32_e32 v0, 0x3f80, v0
	v_lshlrev_b32_e32 v2, 1, v12
	v_and_b32_e32 v2, 62, v2
	v_lshl_add_u32 v3, v2, 1, v0
	v_lshlrev_b32_e32 v4, 2, v2
	v_readfirstlane_b32 s10, v12
	v_mov_b32_e32 v10, 0
	v_mov_b32_e32 v11, 0
	s_nop 3
	s_lshr_b32 s10, s10, 12
	s_and_b32 s13, s10, 1
	s_lshl_b32 s10, s10, 6
	s_mul_i32 s11, s13, 63
	s_add_i32 s10, s10, s11
	s_lshl_b32 s11, s10, 8
	s_lshl_b32 s10, s10, 14
	s_lshl_b32 s12, s13, 15
	s_sub_i32 s12, 0x4000, s12
	s_lshl_b32 s13, s13, 9
	s_sub_i32 s13, 0x100, s13
	s_waitcnt vmcnt(0) lgkmcnt(0)
	v_add_u32_e32 v14, s10, v3
	v_add_u32_e32 v15, s11, v4
	global_load_dword v20, v14, s[2:3]
	global_load_dwordx2 v[52:53], v15, s[6:7]
	s_add_i32 s10, s10, s12
	s_add_i32 s11, s11, s13
	v_add_u32_e32 v14, s10, v3
	v_add_u32_e32 v15, s11, v4
	global_load_dword v21, v14, s[2:3]
	global_load_dwordx2 v[54:55], v15, s[6:7]
	s_add_i32 s10, s10, s12
	s_add_i32 s11, s11, s13
	v_add_u32_e32 v14, s10, v3
	v_add_u32_e32 v15, s11, v4
	global_load_dword v22, v14, s[2:3]
	global_load_dwordx2 v[56:57], v15, s[6:7]
	s_add_i32 s10, s10, s12
	s_add_i32 s11, s11, s13
	v_add_u32_e32 v14, s10, v3
	v_add_u32_e32 v15, s11, v4
	global_load_dword v23, v14, s[2:3]
	global_load_dwordx2 v[58:59], v15, s[6:7]
	s_add_i32 s10, s10, s12
	s_add_i32 s11, s11, s13
	v_add_u32_e32 v14, s10, v3
	v_add_u32_e32 v15, s11, v4
	global_load_dword v24, v14, s[2:3]
	global_load_dwordx2 v[60:61], v15, s[6:7]
	s_add_i32 s10, s10, s12
	s_add_i32 s11, s11, s13
	v_add_u32_e32 v14, s10, v3
	v_add_u32_e32 v15, s11, v4
	global_load_dword v25, v14, s[2:3]
	global_load_dwordx2 v[62:63], v15, s[6:7]
	s_add_i32 s10, s10, s12
	s_add_i32 s11, s11, s13
	v_add_u32_e32 v14, s10, v3
	v_add_u32_e32 v15, s11, v4
	global_load_dword v26, v14, s[2:3]
	global_load_dwordx2 v[64:65], v15, s[6:7]
	s_add_i32 s10, s10, s12
	s_add_i32 s11, s11, s13
	v_add_u32_e32 v14, s10, v3
	v_add_u32_e32 v15, s11, v4
	global_load_dword v27, v14, s[2:3]
	global_load_dwordx2 v[66:67], v15, s[6:7]
	s_add_i32 s10, s10, s12
	s_add_i32 s11, s11, s13
	v_add_u32_e32 v14, s10, v3
	v_add_u32_e32 v15, s11, v4
	global_load_dword v28, v14, s[2:3]
	global_load_dwordx2 v[68:69], v15, s[6:7]
	s_add_i32 s10, s10, s12
	s_add_i32 s11, s11, s13
	v_add_u32_e32 v14, s10, v3
	v_add_u32_e32 v15, s11, v4
	global_load_dword v29, v14, s[2:3]
	global_load_dwordx2 v[70:71], v15, s[6:7]
	s_add_i32 s10, s10, s12
	s_add_i32 s11, s11, s13
	v_add_u32_e32 v14, s10, v3
	v_add_u32_e32 v15, s11, v4
	global_load_dword v30, v14, s[2:3]
	global_load_dwordx2 v[72:73], v15, s[6:7]
	s_add_i32 s10, s10, s12
	s_add_i32 s11, s11, s13
	v_add_u32_e32 v14, s10, v3
	v_add_u32_e32 v15, s11, v4
	global_load_dword v31, v14, s[2:3]
	global_load_dwordx2 v[74:75], v15, s[6:7]
	s_add_i32 s10, s10, s12
	s_add_i32 s11, s11, s13
	v_add_u32_e32 v14, s10, v3
	v_add_u32_e32 v15, s11, v4
	global_load_dword v32, v14, s[2:3]
	global_load_dwordx2 v[76:77], v15, s[6:7]
	s_add_i32 s10, s10, s12
	s_add_i32 s11, s11, s13
	v_add_u32_e32 v14, s10, v3
	v_add_u32_e32 v15, s11, v4
	global_load_dword v33, v14, s[2:3]
	global_load_dwordx2 v[78:79], v15, s[6:7]
	s_add_i32 s10, s10, s12
	s_add_i32 s11, s11, s13
	v_add_u32_e32 v14, s10, v3
	v_add_u32_e32 v15, s11, v4
	global_load_dword v34, v14, s[2:3]
	global_load_dwordx2 v[80:81], v15, s[6:7]
	s_add_i32 s10, s10, s12
	s_add_i32 s11, s11, s13
	v_add_u32_e32 v14, s10, v3
	v_add_u32_e32 v15, s11, v4
	global_load_dword v35, v14, s[2:3]
	global_load_dwordx2 v[82:83], v15, s[6:7]
	s_add_i32 s10, s10, s12
	s_add_i32 s11, s11, s13
	v_add_u32_e32 v14, s10, v3
	v_add_u32_e32 v15, s11, v4
	global_load_dword v36, v14, s[2:3]
	global_load_dwordx2 v[84:85], v15, s[6:7]
	s_add_i32 s10, s10, s12
	s_add_i32 s11, s11, s13
	v_add_u32_e32 v14, s10, v3
	v_add_u32_e32 v15, s11, v4
	global_load_dword v37, v14, s[2:3]
	global_load_dwordx2 v[86:87], v15, s[6:7]
	s_add_i32 s10, s10, s12
	s_add_i32 s11, s11, s13
	v_add_u32_e32 v14, s10, v3
	v_add_u32_e32 v15, s11, v4
	global_load_dword v38, v14, s[2:3]
	global_load_dwordx2 v[88:89], v15, s[6:7]
	s_add_i32 s10, s10, s12
	s_add_i32 s11, s11, s13
	v_add_u32_e32 v14, s10, v3
	v_add_u32_e32 v15, s11, v4
	global_load_dword v39, v14, s[2:3]
	global_load_dwordx2 v[90:91], v15, s[6:7]
	s_add_i32 s10, s10, s12
	s_add_i32 s11, s11, s13
	v_add_u32_e32 v14, s10, v3
	v_add_u32_e32 v15, s11, v4
	global_load_dword v40, v14, s[2:3]
	global_load_dwordx2 v[92:93], v15, s[6:7]
	s_add_i32 s10, s10, s12
	s_add_i32 s11, s11, s13
	v_add_u32_e32 v14, s10, v3
	v_add_u32_e32 v15, s11, v4
	global_load_dword v41, v14, s[2:3]
	global_load_dwordx2 v[94:95], v15, s[6:7]
	s_add_i32 s10, s10, s12
	s_add_i32 s11, s11, s13
	v_add_u32_e32 v14, s10, v3
	v_add_u32_e32 v15, s11, v4
	global_load_dword v42, v14, s[2:3]
	global_load_dwordx2 v[96:97], v15, s[6:7]
	s_add_i32 s10, s10, s12
	s_add_i32 s11, s11, s13
	v_add_u32_e32 v14, s10, v3
	v_add_u32_e32 v15, s11, v4
	global_load_dword v43, v14, s[2:3]
	global_load_dwordx2 v[98:99], v15, s[6:7]
	s_add_i32 s10, s10, s12
	s_add_i32 s11, s11, s13
	v_add_u32_e32 v14, s10, v3
	v_add_u32_e32 v15, s11, v4
	global_load_dword v44, v14, s[2:3]
	global_load_dwordx2 v[100:101], v15, s[6:7]
	s_add_i32 s10, s10, s12
	s_add_i32 s11, s11, s13
	v_add_u32_e32 v14, s10, v3
	v_add_u32_e32 v15, s11, v4
	global_load_dword v45, v14, s[2:3]
	global_load_dwordx2 v[102:103], v15, s[6:7]
	s_add_i32 s10, s10, s12
	s_add_i32 s11, s11, s13
	v_add_u32_e32 v14, s10, v3
	v_add_u32_e32 v15, s11, v4
	global_load_dword v46, v14, s[2:3]
	global_load_dwordx2 v[104:105], v15, s[6:7]
	s_add_i32 s10, s10, s12
	s_add_i32 s11, s11, s13
	v_add_u32_e32 v14, s10, v3
	v_add_u32_e32 v15, s11, v4
	global_load_dword v47, v14, s[2:3]
	global_load_dwordx2 v[106:107], v15, s[6:7]
	s_add_i32 s10, s10, s12
	s_add_i32 s11, s11, s13
	v_add_u32_e32 v14, s10, v3
	v_add_u32_e32 v15, s11, v4
	global_load_dword v48, v14, s[2:3]
	global_load_dwordx2 v[108:109], v15, s[6:7]
	s_add_i32 s10, s10, s12
	s_add_i32 s11, s11, s13
	v_add_u32_e32 v14, s10, v3
	v_add_u32_e32 v15, s11, v4
	global_load_dword v49, v14, s[2:3]
	global_load_dwordx2 v[110:111], v15, s[6:7]
	s_add_i32 s10, s10, s12
	s_add_i32 s11, s11, s13
	v_add_u32_e32 v14, s10, v3
	v_add_u32_e32 v15, s11, v4
	global_load_dword v50, v14, s[2:3]
	global_load_dwordx2 v[112:113], v15, s[6:7]
	s_add_i32 s10, s10, s12
	s_add_i32 s11, s11, s13
	v_add_u32_e32 v14, s10, v3
	v_add_u32_e32 v15, s11, v4
	global_load_dword v51, v14, s[2:3]
	global_load_dwordx2 v[114:115], v15, s[6:7]
	s_add_i32 s10, s10, s12
	s_add_i32 s11, s11, s13
	s_lshl_b32 vcc_lo, s12, 5
	s_sub_i32 s10, s10, vcc_lo
	s_waitcnt vmcnt(0)
; __device__ __forceinline__ unsigned cvt_pk_bf16(float lo, float hi) { unsigned r; asm volatile("v_cvt_pk_bf16_f32 %0, %1, %2" : "=v"(r) : "v"(lo), "v"(hi)); return r; }
; __device__ __forceinline__ void scan_phase(const Args& a) {
;     ...
;         const int seq = g >> 12, e2 = g & 4095, v = e2 >> 5, k2 = (e2 & 31) * 2, dir = seq & 1; float s0 = 0.f, s1 = 0.f;
; #pragma unroll 8
;         for (int step = 0; step < 64; ++step) { const int c = dir ? 63 - step : step; const size_t idx = (size_t)seq * 64 + c;
;             const unsigned kw = *(const unsigned*)(kvt + idx * 8192 + v * 64 + k2); const f32x2 kv = (f32x2){bflo(kw), bfhi(kw)}; const f32x2 d = *(const f32x2*)(dec + idx * 64 + k2);
;             *(unsigned*)(st + idx * 8192 + v * 64 + k2) = cvt_pk_bf16(s0, s1);
;             s0 = d.x * s0 + kv.x; s1 = d.y * s1 + kv.y; }
	v_cvt_pk_bf16_f32 v16, v10, v11
	v_add_u32_e32 v14, s10, v3
	v_lshlrev_b32_e32 v18, 16, v20
	v_and_b32_e32 v19, 0xffff0000, v20
	global_store_dword v14, v16, s[8:9]
	v_pk_fma_f32 v[10:11], v[10:11], v[52:53], v[18:19]
	s_add_i32 s10, s10, s12
	v_cvt_pk_bf16_f32 v17, v10, v11
	v_add_u32_e32 v14, s10, v3
	v_lshlrev_b32_e32 v18, 16, v21
	v_and_b32_e32 v19, 0xffff0000, v21
	global_store_dword v14, v17, s[8:9]
	v_pk_fma_f32 v[10:11], v[10:11], v[54:55], v[18:19]
	s_add_i32 s10, s10, s12
	v_cvt_pk_bf16_f32 v16, v10, v11
	v_add_u32_e32 v14, s10, v3
	v_lshlrev_b32_e32 v18, 16, v22
	v_and_b32_e32 v19, 0xffff0000, v22
	global_store_dword v14, v16, s[8:9]
	v_pk_fma_f32 v[10:11], v[10:11], v[56:57], v[18:19]
	s_add_i32 s10, s10, s12
	v_cvt_pk_bf16_f32 v17, v10, v11
	v_add_u32_e32 v14, s10, v3
	v_lshlrev_b32_e32 v18, 16, v23
	v_and_b32_e32 v19, 0xffff0000, v23
	global_store_dword v14, v17, s[8:9]
	v_pk_fma_f32 v[10:11], v[10:11], v[58:59], v[18:19]
	s_add_i32 s10, s10, s12
	v_cvt_pk_bf16_f32 v16, v10, v11
	v_add_u32_e32 v14, s10, v3
	v_lshlrev_b32_e32 v18, 16, v24
	v_and_b32_e32 v19, 0xffff0000, v24
	global_store_dword v14, v16, s[8:9]
	v_pk_fma_f32 v[10:11], v[10:11], v[60:61], v[18:19]
	s_add_i32 s10, s10, s12
	v_cvt_pk_bf16_f32 v17, v10, v11
	v_add_u32_e32 v14, s10, v3
	v_lshlrev_b32_e32 v18, 16, v25
	v_and_b32_e32 v19, 0xffff0000, v25
	global_store_dword v14, v17, s[8:9]
	v_pk_fma_f32 v[10:11], v[10:11], v[62:63], v[18:19]
	s_add_i32 s10, s10, s12
	v_cvt_pk_bf16_f32 v16, v10, v11
	v_add_u32_e32 v14, s10, v3
	v_lshlrev_b32_e32 v18, 16, v26
	v_and_b32_e32 v19, 0xffff0000, v26
	global_store_dword v14, v16, s[8:9]
	v_pk_fma_f32 v[10:11], v[10:11], v[64:65], v[18:19]
	s_add_i32 s10, s10, s12
	v_cvt_pk_bf16_f32 v17, v10, v11
	v_add_u32_e32 v14, s10, v3
	v_lshlrev_b32_e32 v18, 16, v27
	v_and_b32_e32 v19, 0xffff0000, v27
	global_store_dword v14, v17, s[8:9]
	v_pk_fma_f32 v[10:11], v[10:11], v[66:67], v[18:19]
	s_add_i32 s10, s10, s12
	v_cvt_pk_bf16_f32 v16, v10, v11
	v_add_u32_e32 v14, s10, v3
	v_lshlrev_b32_e32 v18, 16, v28
	v_and_b32_e32 v19, 0xffff0000, v28
	global_store_dword v14, v16, s[8:9]
	v_pk_fma_f32 v[10:11], v[10:11], v[68:69], v[18:19]
	s_add_i32 s10, s10, s12
	v_cvt_pk_bf16_f32 v17, v10, v11
	v_add_u32_e32 v14, s10, v3
	v_lshlrev_b32_e32 v18, 16, v29
	v_and_b32_e32 v19, 0xffff0000, v29
	global_store_dword v14, v17, s[8:9]
	v_pk_fma_f32 v[10:11], v[10:11], v[70:71], v[18:19]
	s_add_i32 s10, s10, s12
	v_cvt_pk_bf16_f32 v16, v10, v11
	v_add_u32_e32 v14, s10, v3
	v_lshlrev_b32_e32 v18, 16, v30
	v_and_b32_e32 v19, 0xffff0000, v30
	global_store_dword v14, v16, s[8:9]
	v_pk_fma_f32 v[10:11], v[10:11], v[72:73], v[18:19]
	s_add_i32 s10, s10, s12
	v_cvt_pk_bf16_f32 v17, v10, v11
	v_add_u32_e32 v14, s10, v3
	v_lshlrev_b32_e32 v18, 16, v31
	v_and_b32_e32 v19, 0xffff0000, v31
	global_store_dword v14, v17, s[8:9]
	v_pk_fma_f32 v[10:11], v[10:11], v[74:75], v[18:19]
	s_add_i32 s10, s10, s12
	v_cvt_pk_bf16_f32 v16, v10, v11
	v_add_u32_e32 v14, s10, v3
	v_lshlrev_b32_e32 v18, 16, v32
	v_and_b32_e32 v19, 0xffff0000, v32
	global_store_dword v14, v16, s[8:9]
	v_pk_fma_f32 v[10:11], v[10:11], v[76:77], v[18:19]
	s_add_i32 s10, s10, s12
	v_cvt_pk_bf16_f32 v17, v10, v11
	v_add_u32_e32 v14, s10, v3
	v_lshlrev_b32_e32 v18, 16, v33
	v_and_b32_e32 v19, 0xffff0000, v33
	global_store_dword v14, v17, s[8:9]
	v_pk_fma_f32 v[10:11], v[10:11], v[78:79], v[18:19]
	s_add_i32 s10, s10, s12
	v_cvt_pk_bf16_f32 v16, v10, v11
	v_add_u32_e32 v14, s10, v3
	v_lshlrev_b32_e32 v18, 16, v34
	v_and_b32_e32 v19, 0xffff0000, v34
	global_store_dword v14, v16, s[8:9]
	v_pk_fma_f32 v[10:11], v[10:11], v[80:81], v[18:19]
	s_add_i32 s10, s10, s12
	v_cvt_pk_bf16_f32 v17, v10, v11
	v_add_u32_e32 v14, s10, v3
	v_lshlrev_b32_e32 v18, 16, v35
	v_and_b32_e32 v19, 0xffff0000, v35
	global_store_dword v14, v17, s[8:9]
	v_pk_fma_f32 v[10:11], v[10:11], v[82:83], v[18:19]
	s_add_i32 s10, s10, s12
	v_cvt_pk_bf16_f32 v16, v10, v11
	v_add_u32_e32 v14, s10, v3
	v_lshlrev_b32_e32 v18, 16, v36
	v_and_b32_e32 v19, 0xffff0000, v36
	global_store_dword v14, v16, s[8:9]
	v_pk_fma_f32 v[10:11], v[10:11], v[84:85], v[18:19]
	s_add_i32 s10, s10, s12
	v_cvt_pk_bf16_f32 v17, v10, v11
	v_add_u32_e32 v14, s10, v3
	v_lshlrev_b32_e32 v18, 16, v37
	v_and_b32_e32 v19, 0xffff0000, v37
	global_store_dword v14, v17, s[8:9]
	v_pk_fma_f32 v[10:11], v[10:11], v[86:87], v[18:19]
	s_add_i32 s10, s10, s12
	v_cvt_pk_bf16_f32 v16, v10, v11
	v_add_u32_e32 v14, s10, v3
	v_lshlrev_b32_e32 v18, 16, v38
	v_and_b32_e32 v19, 0xffff0000, v38
	global_store_dword v14, v16, s[8:9]
	v_pk_fma_f32 v[10:11], v[10:11], v[88:89], v[18:19]
	s_add_i32 s10, s10, s12
	v_cvt_pk_bf16_f32 v17, v10, v11
	v_add_u32_e32 v14, s10, v3
	v_lshlrev_b32_e32 v18, 16, v39
	v_and_b32_e32 v19, 0xffff0000, v39
	global_store_dword v14, v17, s[8:9]
	v_pk_fma_f32 v[10:11], v[10:11], v[90:91], v[18:19]
	s_add_i32 s10, s10, s12
	v_cvt_pk_bf16_f32 v16, v10, v11
	v_add_u32_e32 v14, s10, v3
	v_lshlrev_b32_e32 v18, 16, v40
	v_and_b32_e32 v19, 0xffff0000, v40
	global_store_dword v14, v16, s[8:9]
	v_pk_fma_f32 v[10:11], v[10:11], v[92:93], v[18:19]
	s_add_i32 s10, s10, s12
	v_cvt_pk_bf16_f32 v17, v10, v11
	v_add_u32_e32 v14, s10, v3
	v_lshlrev_b32_e32 v18, 16, v41
	v_and_b32_e32 v19, 0xffff0000, v41
	global_store_dword v14, v17, s[8:9]
	v_pk_fma_f32 v[10:11], v[10:11], v[94:95], v[18:19]
	s_add_i32 s10, s10, s12
	v_cvt_pk_bf16_f32 v16, v10, v11
	v_add_u32_e32 v14, s10, v3
	v_lshlrev_b32_e32 v18, 16, v42
	v_and_b32_e32 v19, 0xffff0000, v42
	global_store_dword v14, v16, s[8:9]
	v_pk_fma_f32 v[10:11], v[10:11], v[96:97], v[18:19]
	s_add_i32 s10, s10, s12
	v_cvt_pk_bf16_f32 v17, v10, v11
; __device__ __forceinline__ unsigned cvt_pk_bf16(float lo, float hi) { unsigned r; asm volatile("v_cvt_pk_bf16_f32 %0, %1, %2" : "=v"(r) : "v"(lo), "v"(hi)); return r; }
; __device__ __forceinline__ void scan_phase(const Args& a) {
;     ...
;         const int seq = g >> 12, e2 = g & 4095, v = e2 >> 5, k2 = (e2 & 31) * 2, dir = seq & 1; float s0 = 0.f, s1 = 0.f;
; #pragma unroll 8
;         for (int step = 0; step < 64; ++step) { const int c = dir ? 63 - step : step; const size_t idx = (size_t)seq * 64 + c;
;             const unsigned kw = *(const unsigned*)(kvt + idx * 8192 + v * 64 + k2); const f32x2 kv = (f32x2){bflo(kw), bfhi(kw)}; const f32x2 d = *(const f32x2*)(dec + idx * 64 + k2);
;             *(unsigned*)(st + idx * 8192 + v * 64 + k2) = cvt_pk_bf16(s0, s1);
;             s0 = d.x * s0 + kv.x; s1 = d.y * s1 + kv.y; }
	v_add_u32_e32 v14, s10, v3
	v_lshlrev_b32_e32 v18, 16, v43
	v_and_b32_e32 v19, 0xffff0000, v43
	global_store_dword v14, v17, s[8:9]
	v_pk_fma_f32 v[10:11], v[10:11], v[98:99], v[18:19]
	s_add_i32 s10, s10, s12
	v_cvt_pk_bf16_f32 v16, v10, v11
	v_add_u32_e32 v14, s10, v3
	v_lshlrev_b32_e32 v18, 16, v44
	v_and_b32_e32 v19, 0xffff0000, v44
	global_store_dword v14, v16, s[8:9]
	v_pk_fma_f32 v[10:11], v[10:11], v[100:101], v[18:19]
	s_add_i32 s10, s10, s12
	v_cvt_pk_bf16_f32 v17, v10, v11
	v_add_u32_e32 v14, s10, v3
	v_lshlrev_b32_e32 v18, 16, v45
	v_and_b32_e32 v19, 0xffff0000, v45
	global_store_dword v14, v17, s[8:9]
	v_pk_fma_f32 v[10:11], v[10:11], v[102:103], v[18:19]
	s_add_i32 s10, s10, s12
	v_cvt_pk_bf16_f32 v16, v10, v11
	v_add_u32_e32 v14, s10, v3
	v_lshlrev_b32_e32 v18, 16, v46
	v_and_b32_e32 v19, 0xffff0000, v46
	global_store_dword v14, v16, s[8:9]
	v_pk_fma_f32 v[10:11], v[10:11], v[104:105], v[18:19]
	s_add_i32 s10, s10, s12
	v_cvt_pk_bf16_f32 v17, v10, v11
	v_add_u32_e32 v14, s10, v3
	v_lshlrev_b32_e32 v18, 16, v47
	v_and_b32_e32 v19, 0xffff0000, v47
	global_store_dword v14, v17, s[8:9]
	v_pk_fma_f32 v[10:11], v[10:11], v[106:107], v[18:19]
	s_add_i32 s10, s10, s12
	v_cvt_pk_bf16_f32 v16, v10, v11
	v_add_u32_e32 v14, s10, v3
	v_lshlrev_b32_e32 v18, 16, v48
	v_and_b32_e32 v19, 0xffff0000, v48
	global_store_dword v14, v16, s[8:9]
	v_pk_fma_f32 v[10:11], v[10:11], v[108:109], v[18:19]
	s_add_i32 s10, s10, s12
	v_cvt_pk_bf16_f32 v17, v10, v11
	v_add_u32_e32 v14, s10, v3
	v_lshlrev_b32_e32 v18, 16, v49
	v_and_b32_e32 v19, 0xffff0000, v49
	global_store_dword v14, v17, s[8:9]
	v_pk_fma_f32 v[10:11], v[10:11], v[110:111], v[18:19]
	s_add_i32 s10, s10, s12
	v_cvt_pk_bf16_f32 v16, v10, v11
	v_add_u32_e32 v14, s10, v3
	v_lshlrev_b32_e32 v18, 16, v50
	v_and_b32_e32 v19, 0xffff0000, v50
	global_store_dword v14, v16, s[8:9]
	v_pk_fma_f32 v[10:11], v[10:11], v[112:113], v[18:19]
	s_add_i32 s10, s10, s12
	v_cvt_pk_bf16_f32 v17, v10, v11
	v_add_u32_e32 v14, s10, v3
	v_lshlrev_b32_e32 v18, 16, v51
	v_and_b32_e32 v19, 0xffff0000, v51
	global_store_dword v14, v17, s[8:9]
	v_pk_fma_f32 v[10:11], v[10:11], v[114:115], v[18:19]
	s_add_i32 s10, s10, s12
	v_add_u32_e32 v14, s10, v3
	v_add_u32_e32 v15, s11, v4
	global_load_dword v20, v14, s[2:3]
	global_load_dwordx2 v[52:53], v15, s[6:7]
	s_add_i32 s10, s10, s12
	s_add_i32 s11, s11, s13
	v_add_u32_e32 v14, s10, v3
	v_add_u32_e32 v15, s11, v4
	global_load_dword v21, v14, s[2:3]
	global_load_dwordx2 v[54:55], v15, s[6:7]
	s_add_i32 s10, s10, s12
	s_add_i32 s11, s11, s13
	v_add_u32_e32 v14, s10, v3
	v_add_u32_e32 v15, s11, v4
	global_load_dword v22, v14, s[2:3]
	global_load_dwordx2 v[56:57], v15, s[6:7]
	s_add_i32 s10, s10, s12
	s_add_i32 s11, s11, s13
	v_add_u32_e32 v14, s10, v3
	v_add_u32_e32 v15, s11, v4
	global_load_dword v23, v14, s[2:3]
	global_load_dwordx2 v[58:59], v15, s[6:7]
	s_add_i32 s10, s10, s12
	s_add_i32 s11, s11, s13
	v_add_u32_e32 v14, s10, v3
	v_add_u32_e32 v15, s11, v4
	global_load_dword v24, v14, s[2:3]
	global_load_dwordx2 v[60:61], v15, s[6:7]
	s_add_i32 s10, s10, s12
	s_add_i32 s11, s11, s13
	v_add_u32_e32 v14, s10, v3
	v_add_u32_e32 v15, s11, v4
	global_load_dword v25, v14, s[2:3]
	global_load_dwordx2 v[62:63], v15, s[6:7]
	s_add_i32 s10, s10, s12
	s_add_i32 s11, s11, s13
	v_add_u32_e32 v14, s10, v3
	v_add_u32_e32 v15, s11, v4
	global_load_dword v26, v14, s[2:3]
	global_load_dwordx2 v[64:65], v15, s[6:7]
	s_add_i32 s10, s10, s12
	s_add_i32 s11, s11, s13
	v_add_u32_e32 v14, s10, v3
	v_add_u32_e32 v15, s11, v4
	global_load_dword v27, v14, s[2:3]
	global_load_dwordx2 v[66:67], v15, s[6:7]
	s_add_i32 s10, s10, s12
	s_add_i32 s11, s11, s13
	v_add_u32_e32 v14, s10, v3
	v_add_u32_e32 v15, s11, v4
	global_load_dword v28, v14, s[2:3]
	global_load_dwordx2 v[68:69], v15, s[6:7]
	s_add_i32 s10, s10, s12
	s_add_i32 s11, s11, s13
	v_add_u32_e32 v14, s10, v3
	v_add_u32_e32 v15, s11, v4
	global_load_dword v29, v14, s[2:3]
	global_load_dwordx2 v[70:71], v15, s[6:7]
	s_add_i32 s10, s10, s12
	s_add_i32 s11, s11, s13
	v_add_u32_e32 v14, s10, v3
	v_add_u32_e32 v15, s11, v4
	global_load_dword v30, v14, s[2:3]
	global_load_dwordx2 v[72:73], v15, s[6:7]
	s_add_i32 s10, s10, s12
	s_add_i32 s11, s11, s13
	v_add_u32_e32 v14, s10, v3
	v_add_u32_e32 v15, s11, v4
	global_load_dword v31, v14, s[2:3]
	global_load_dwordx2 v[74:75], v15, s[6:7]
	s_add_i32 s10, s10, s12
	s_add_i32 s11, s11, s13
	v_add_u32_e32 v14, s10, v3
	v_add_u32_e32 v15, s11, v4
	global_load_dword v32, v14, s[2:3]
	global_load_dwordx2 v[76:77], v15, s[6:7]
	s_add_i32 s10, s10, s12
	s_add_i32 s11, s11, s13
	v_add_u32_e32 v14, s10, v3
	v_add_u32_e32 v15, s11, v4
	global_load_dword v33, v14, s[2:3]
	global_load_dwordx2 v[78:79], v15, s[6:7]
	s_add_i32 s10, s10, s12
	s_add_i32 s11, s11, s13
	v_add_u32_e32 v14, s10, v3
	v_add_u32_e32 v15, s11, v4
	global_load_dword v34, v14, s[2:3]
	global_load_dwordx2 v[80:81], v15, s[6:7]
	s_add_i32 s10, s10, s12
	s_add_i32 s11, s11, s13
	v_add_u32_e32 v14, s10, v3
	v_add_u32_e32 v15, s11, v4
	global_load_dword v35, v14, s[2:3]
	global_load_dwordx2 v[82:83], v15, s[6:7]
	s_add_i32 s10, s10, s12
	s_add_i32 s11, s11, s13
	v_add_u32_e32 v14, s10, v3
	v_add_u32_e32 v15, s11, v4
	global_load_dword v36, v14, s[2:3]
	global_load_dwordx2 v[84:85], v15, s[6:7]
	s_add_i32 s10, s10, s12
	s_add_i32 s11, s11, s13
	v_add_u32_e32 v14, s10, v3
	v_add_u32_e32 v15, s11, v4
	global_load_dword v37, v14, s[2:3]
	global_load_dwordx2 v[86:87], v15, s[6:7]
	s_add_i32 s10, s10, s12
	s_add_i32 s11, s11, s13
	v_add_u32_e32 v14, s10, v3
	v_add_u32_e32 v15, s11, v4
	global_load_dword v38, v14, s[2:3]
	global_load_dwordx2 v[88:89], v15, s[6:7]
; __device__ __forceinline__ unsigned cvt_pk_bf16(float lo, float hi) { unsigned r; asm volatile("v_cvt_pk_bf16_f32 %0, %1, %2" : "=v"(r) : "v"(lo), "v"(hi)); return r; }
; __device__ __forceinline__ void scan_phase(const Args& a) {
;     ...
;         const int seq = g >> 12, e2 = g & 4095, v = e2 >> 5, k2 = (e2 & 31) * 2, dir = seq & 1; float s0 = 0.f, s1 = 0.f;
; #pragma unroll 8
;         for (int step = 0; step < 64; ++step) { const int c = dir ? 63 - step : step; const size_t idx = (size_t)seq * 64 + c;
;             const unsigned kw = *(const unsigned*)(kvt + idx * 8192 + v * 64 + k2); const f32x2 kv = (f32x2){bflo(kw), bfhi(kw)}; const f32x2 d = *(const f32x2*)(dec + idx * 64 + k2);
;             *(unsigned*)(st + idx * 8192 + v * 64 + k2) = cvt_pk_bf16(s0, s1);
;             s0 = d.x * s0 + kv.x; s1 = d.y * s1 + kv.y; }
	s_add_i32 s10, s10, s12
	s_add_i32 s11, s11, s13
	v_add_u32_e32 v14, s10, v3
	v_add_u32_e32 v15, s11, v4
	global_load_dword v39, v14, s[2:3]
	global_load_dwordx2 v[90:91], v15, s[6:7]
	s_add_i32 s10, s10, s12
	s_add_i32 s11, s11, s13
	v_add_u32_e32 v14, s10, v3
	v_add_u32_e32 v15, s11, v4
	global_load_dword v40, v14, s[2:3]
	global_load_dwordx2 v[92:93], v15, s[6:7]
	s_add_i32 s10, s10, s12
	s_add_i32 s11, s11, s13
	v_add_u32_e32 v14, s10, v3
	v_add_u32_e32 v15, s11, v4
	global_load_dword v41, v14, s[2:3]
	global_load_dwordx2 v[94:95], v15, s[6:7]
	s_add_i32 s10, s10, s12
	s_add_i32 s11, s11, s13
	v_add_u32_e32 v14, s10, v3
	v_add_u32_e32 v15, s11, v4
	global_load_dword v42, v14, s[2:3]
	global_load_dwordx2 v[96:97], v15, s[6:7]
	s_add_i32 s10, s10, s12
	s_add_i32 s11, s11, s13
	v_add_u32_e32 v14, s10, v3
	v_add_u32_e32 v15, s11, v4
	global_load_dword v43, v14, s[2:3]
	global_load_dwordx2 v[98:99], v15, s[6:7]
	s_add_i32 s10, s10, s12
	s_add_i32 s11, s11, s13
	v_add_u32_e32 v14, s10, v3
	v_add_u32_e32 v15, s11, v4
	global_load_dword v44, v14, s[2:3]
	global_load_dwordx2 v[100:101], v15, s[6:7]
	s_add_i32 s10, s10, s12
	s_add_i32 s11, s11, s13
	v_add_u32_e32 v14, s10, v3
	v_add_u32_e32 v15, s11, v4
	global_load_dword v45, v14, s[2:3]
	global_load_dwordx2 v[102:103], v15, s[6:7]
	s_add_i32 s10, s10, s12
	s_add_i32 s11, s11, s13
	v_add_u32_e32 v14, s10, v3
	v_add_u32_e32 v15, s11, v4
	global_load_dword v46, v14, s[2:3]
	global_load_dwordx2 v[104:105], v15, s[6:7]
	s_add_i32 s10, s10, s12
	s_add_i32 s11, s11, s13
	v_add_u32_e32 v14, s10, v3
	v_add_u32_e32 v15, s11, v4
	global_load_dword v47, v14, s[2:3]
	global_load_dwordx2 v[106:107], v15, s[6:7]
	s_add_i32 s10, s10, s12
	s_add_i32 s11, s11, s13
	v_add_u32_e32 v14, s10, v3
	v_add_u32_e32 v15, s11, v4
	global_load_dword v48, v14, s[2:3]
	global_load_dwordx2 v[108:109], v15, s[6:7]
	s_add_i32 s10, s10, s12
	s_add_i32 s11, s11, s13
	v_add_u32_e32 v14, s10, v3
	v_add_u32_e32 v15, s11, v4
	global_load_dword v49, v14, s[2:3]
	global_load_dwordx2 v[110:111], v15, s[6:7]
	s_add_i32 s10, s10, s12
	s_add_i32 s11, s11, s13
	v_add_u32_e32 v14, s10, v3
	v_add_u32_e32 v15, s11, v4
	global_load_dword v50, v14, s[2:3]
	global_load_dwordx2 v[112:113], v15, s[6:7]
	s_add_i32 s10, s10, s12
	s_add_i32 s11, s11, s13
	v_add_u32_e32 v14, s10, v3
	v_add_u32_e32 v15, s11, v4
	global_load_dword v51, v14, s[2:3]
	global_load_dwordx2 v[114:115], v15, s[6:7]
	s_add_i32 s10, s10, s12
	s_add_i32 s11, s11, s13
	s_lshl_b32 vcc_lo, s12, 5
	s_sub_i32 s10, s10, vcc_lo
	s_waitcnt vmcnt(0)
	v_cvt_pk_bf16_f32 v16, v10, v11
	v_add_u32_e32 v14, s10, v3
	v_lshlrev_b32_e32 v18, 16, v20
	v_and_b32_e32 v19, 0xffff0000, v20
	global_store_dword v14, v16, s[8:9]
	v_pk_fma_f32 v[10:11], v[10:11], v[52:53], v[18:19]
	s_add_i32 s10, s10, s12
	v_cvt_pk_bf16_f32 v17, v10, v11
	v_add_u32_e32 v14, s10, v3
	v_lshlrev_b32_e32 v18, 16, v21
	v_and_b32_e32 v19, 0xffff0000, v21
	global_store_dword v14, v17, s[8:9]
	v_pk_fma_f32 v[10:11], v[10:11], v[54:55], v[18:19]
	s_add_i32 s10, s10, s12
	v_cvt_pk_bf16_f32 v16, v10, v11
	v_add_u32_e32 v14, s10, v3
	v_lshlrev_b32_e32 v18, 16, v22
	v_and_b32_e32 v19, 0xffff0000, v22
	global_store_dword v14, v16, s[8:9]
	v_pk_fma_f32 v[10:11], v[10:11], v[56:57], v[18:19]
	s_add_i32 s10, s10, s12
	v_cvt_pk_bf16_f32 v17, v10, v11
	v_add_u32_e32 v14, s10, v3
	v_lshlrev_b32_e32 v18, 16, v23
	v_and_b32_e32 v19, 0xffff0000, v23
	global_store_dword v14, v17, s[8:9]
	v_pk_fma_f32 v[10:11], v[10:11], v[58:59], v[18:19]
	s_add_i32 s10, s10, s12
	v_cvt_pk_bf16_f32 v16, v10, v11
	v_add_u32_e32 v14, s10, v3
	v_lshlrev_b32_e32 v18, 16, v24
	v_and_b32_e32 v19, 0xffff0000, v24
	global_store_dword v14, v16, s[8:9]
	v_pk_fma_f32 v[10:11], v[10:11], v[60:61], v[18:19]
	s_add_i32 s10, s10, s12
	v_cvt_pk_bf16_f32 v17, v10, v11
	v_add_u32_e32 v14, s10, v3
	v_lshlrev_b32_e32 v18, 16, v25
	v_and_b32_e32 v19, 0xffff0000, v25
	global_store_dword v14, v17, s[8:9]
	v_pk_fma_f32 v[10:11], v[10:11], v[62:63], v[18:19]
	s_add_i32 s10, s10, s12
	v_cvt_pk_bf16_f32 v16, v10, v11
	v_add_u32_e32 v14, s10, v3
	v_lshlrev_b32_e32 v18, 16, v26
	v_and_b32_e32 v19, 0xffff0000, v26
	global_store_dword v14, v16, s[8:9]
	v_pk_fma_f32 v[10:11], v[10:11], v[64:65], v[18:19]
	s_add_i32 s10, s10, s12
	v_cvt_pk_bf16_f32 v17, v10, v11
	v_add_u32_e32 v14, s10, v3
	v_lshlrev_b32_e32 v18, 16, v27
	v_and_b32_e32 v19, 0xffff0000, v27
	global_store_dword v14, v17, s[8:9]
	v_pk_fma_f32 v[10:11], v[10:11], v[66:67], v[18:19]
	s_add_i32 s10, s10, s12
	v_cvt_pk_bf16_f32 v16, v10, v11
	v_add_u32_e32 v14, s10, v3
	v_lshlrev_b32_e32 v18, 16, v28
	v_and_b32_e32 v19, 0xffff0000, v28
	global_store_dword v14, v16, s[8:9]
	v_pk_fma_f32 v[10:11], v[10:11], v[68:69], v[18:19]
	s_add_i32 s10, s10, s12
	v_cvt_pk_bf16_f32 v17, v10, v11
	v_add_u32_e32 v14, s10, v3
	v_lshlrev_b32_e32 v18, 16, v29
	v_and_b32_e32 v19, 0xffff0000, v29
	global_store_dword v14, v17, s[8:9]
	v_pk_fma_f32 v[10:11], v[10:11], v[70:71], v[18:19]
	s_add_i32 s10, s10, s12
	v_cvt_pk_bf16_f32 v16, v10, v11
	v_add_u32_e32 v14, s10, v3
	v_lshlrev_b32_e32 v18, 16, v30
	v_and_b32_e32 v19, 0xffff0000, v30
	global_store_dword v14, v16, s[8:9]
	v_pk_fma_f32 v[10:11], v[10:11], v[72:73], v[18:19]
	s_add_i32 s10, s10, s12
	v_cvt_pk_bf16_f32 v17, v10, v11
; __device__ __forceinline__ unsigned cvt_pk_bf16(float lo, float hi) { unsigned r; asm volatile("v_cvt_pk_bf16_f32 %0, %1, %2" : "=v"(r) : "v"(lo), "v"(hi)); return r; }
; __device__ __forceinline__ int otid() { int t = threadIdx.x; asm volatile("" : "+v"(t)); return t; }
; __device__ __forceinline__ void scan_phase(const Args& a) {
;     const bf16_t* kvt = (const bf16_t*)(a.ws + WS_KVT); const float* dec = (const float*)(a.ws + WS_DEC); bf16_t* st = (bf16_t*)(a.ws + WS_ST);
;     const int tid = otid();
;     for (int g = blockIdx.x * NTHR + tid; g < 32 * 4096; g += gridDim.x * NTHR) {
;         const int seq = g >> 12, e2 = g & 4095, v = e2 >> 5, k2 = (e2 & 31) * 2, dir = seq & 1; float s0 = 0.f, s1 = 0.f;
; #pragma unroll 8
;         for (int step = 0; step < 64; ++step) { const int c = dir ? 63 - step : step; const size_t idx = (size_t)seq * 64 + c;
;             const unsigned kw = *(const unsigned*)(kvt + idx * 8192 + v * 64 + k2); const f32x2 kv = (f32x2){bflo(kw), bfhi(kw)}; const f32x2 d = *(const f32x2*)(dec + idx * 64 + k2);
;             *(unsigned*)(st + idx * 8192 + v * 64 + k2) = cvt_pk_bf16(s0, s1);
;             s0 = d.x * s0 + kv.x; s1 = d.y * s1 + kv.y; }
	v_add_u32_e32 v14, s10, v3
	v_lshlrev_b32_e32 v18, 16, v31
	v_and_b32_e32 v19, 0xffff0000, v31
	global_store_dword v14, v17, s[8:9]
	v_pk_fma_f32 v[10:11], v[10:11], v[74:75], v[18:19]
	s_add_i32 s10, s10, s12
	v_cvt_pk_bf16_f32 v16, v10, v11
	v_add_u32_e32 v14, s10, v3
	v_lshlrev_b32_e32 v18, 16, v32
	v_and_b32_e32 v19, 0xffff0000, v32
	global_store_dword v14, v16, s[8:9]
	v_pk_fma_f32 v[10:11], v[10:11], v[76:77], v[18:19]
	s_add_i32 s10, s10, s12
	v_cvt_pk_bf16_f32 v17, v10, v11
	v_add_u32_e32 v14, s10, v3
	v_lshlrev_b32_e32 v18, 16, v33
	v_and_b32_e32 v19, 0xffff0000, v33
	global_store_dword v14, v17, s[8:9]
	v_pk_fma_f32 v[10:11], v[10:11], v[78:79], v[18:19]
	s_add_i32 s10, s10, s12
	v_cvt_pk_bf16_f32 v16, v10, v11
	v_add_u32_e32 v14, s10, v3
	v_lshlrev_b32_e32 v18, 16, v34
	v_and_b32_e32 v19, 0xffff0000, v34
	global_store_dword v14, v16, s[8:9]
	v_pk_fma_f32 v[10:11], v[10:11], v[80:81], v[18:19]
	s_add_i32 s10, s10, s12
	v_cvt_pk_bf16_f32 v17, v10, v11
	v_add_u32_e32 v14, s10, v3
	v_lshlrev_b32_e32 v18, 16, v35
	v_and_b32_e32 v19, 0xffff0000, v35
	global_store_dword v14, v17, s[8:9]
	v_pk_fma_f32 v[10:11], v[10:11], v[82:83], v[18:19]
	s_add_i32 s10, s10, s12
	v_cvt_pk_bf16_f32 v16, v10, v11
	v_add_u32_e32 v14, s10, v3
	v_lshlrev_b32_e32 v18, 16, v36
	v_and_b32_e32 v19, 0xffff0000, v36
	global_store_dword v14, v16, s[8:9]
	v_pk_fma_f32 v[10:11], v[10:11], v[84:85], v[18:19]
	s_add_i32 s10, s10, s12
	v_cvt_pk_bf16_f32 v17, v10, v11
	v_add_u32_e32 v14, s10, v3
	v_lshlrev_b32_e32 v18, 16, v37
	v_and_b32_e32 v19, 0xffff0000, v37
	global_store_dword v14, v17, s[8:9]
	v_pk_fma_f32 v[10:11], v[10:11], v[86:87], v[18:19]
	s_add_i32 s10, s10, s12
	v_cvt_pk_bf16_f32 v16, v10, v11
	v_add_u32_e32 v14, s10, v3
	v_lshlrev_b32_e32 v18, 16, v38
	v_and_b32_e32 v19, 0xffff0000, v38
	global_store_dword v14, v16, s[8:9]
	v_pk_fma_f32 v[10:11], v[10:11], v[88:89], v[18:19]
	s_add_i32 s10, s10, s12
	v_cvt_pk_bf16_f32 v17, v10, v11
	v_add_u32_e32 v14, s10, v3
	v_lshlrev_b32_e32 v18, 16, v39
	v_and_b32_e32 v19, 0xffff0000, v39
	global_store_dword v14, v17, s[8:9]
	v_pk_fma_f32 v[10:11], v[10:11], v[90:91], v[18:19]
	s_add_i32 s10, s10, s12
	v_cvt_pk_bf16_f32 v16, v10, v11
	v_add_u32_e32 v14, s10, v3
	v_lshlrev_b32_e32 v18, 16, v40
	v_and_b32_e32 v19, 0xffff0000, v40
	global_store_dword v14, v16, s[8:9]
	v_pk_fma_f32 v[10:11], v[10:11], v[92:93], v[18:19]
	s_add_i32 s10, s10, s12
	v_cvt_pk_bf16_f32 v17, v10, v11
	v_add_u32_e32 v14, s10, v3
	v_lshlrev_b32_e32 v18, 16, v41
	v_and_b32_e32 v19, 0xffff0000, v41
	global_store_dword v14, v17, s[8:9]
	v_pk_fma_f32 v[10:11], v[10:11], v[94:95], v[18:19]
	s_add_i32 s10, s10, s12
	v_cvt_pk_bf16_f32 v16, v10, v11
	v_add_u32_e32 v14, s10, v3
	v_lshlrev_b32_e32 v18, 16, v42
	v_and_b32_e32 v19, 0xffff0000, v42
	global_store_dword v14, v16, s[8:9]
	v_pk_fma_f32 v[10:11], v[10:11], v[96:97], v[18:19]
	s_add_i32 s10, s10, s12
	v_cvt_pk_bf16_f32 v17, v10, v11
	v_add_u32_e32 v14, s10, v3
	v_lshlrev_b32_e32 v18, 16, v43
	v_and_b32_e32 v19, 0xffff0000, v43
	global_store_dword v14, v17, s[8:9]
	v_pk_fma_f32 v[10:11], v[10:11], v[98:99], v[18:19]
	s_add_i32 s10, s10, s12
	v_cvt_pk_bf16_f32 v16, v10, v11
	v_add_u32_e32 v14, s10, v3
	v_lshlrev_b32_e32 v18, 16, v44
	v_and_b32_e32 v19, 0xffff0000, v44
	global_store_dword v14, v16, s[8:9]
	v_pk_fma_f32 v[10:11], v[10:11], v[100:101], v[18:19]
	s_add_i32 s10, s10, s12
	v_cvt_pk_bf16_f32 v17, v10, v11
	v_add_u32_e32 v14, s10, v3
	v_lshlrev_b32_e32 v18, 16, v45
	v_and_b32_e32 v19, 0xffff0000, v45
	global_store_dword v14, v17, s[8:9]
	v_pk_fma_f32 v[10:11], v[10:11], v[102:103], v[18:19]
	s_add_i32 s10, s10, s12
	v_cvt_pk_bf16_f32 v16, v10, v11
	v_add_u32_e32 v14, s10, v3
	v_lshlrev_b32_e32 v18, 16, v46
	v_and_b32_e32 v19, 0xffff0000, v46
	global_store_dword v14, v16, s[8:9]
	v_pk_fma_f32 v[10:11], v[10:11], v[104:105], v[18:19]
	s_add_i32 s10, s10, s12
	v_cvt_pk_bf16_f32 v17, v10, v11
	v_add_u32_e32 v14, s10, v3
	v_lshlrev_b32_e32 v18, 16, v47
	v_and_b32_e32 v19, 0xffff0000, v47
	global_store_dword v14, v17, s[8:9]
	v_pk_fma_f32 v[10:11], v[10:11], v[106:107], v[18:19]
	s_add_i32 s10, s10, s12
	v_cvt_pk_bf16_f32 v16, v10, v11
	v_add_u32_e32 v14, s10, v3
	v_lshlrev_b32_e32 v18, 16, v48
	v_and_b32_e32 v19, 0xffff0000, v48
	global_store_dword v14, v16, s[8:9]
	v_pk_fma_f32 v[10:11], v[10:11], v[108:109], v[18:19]
	s_add_i32 s10, s10, s12
	v_cvt_pk_bf16_f32 v17, v10, v11
	v_add_u32_e32 v14, s10, v3
	v_lshlrev_b32_e32 v18, 16, v49
	v_and_b32_e32 v19, 0xffff0000, v49
	global_store_dword v14, v17, s[8:9]
	v_pk_fma_f32 v[10:11], v[10:11], v[110:111], v[18:19]
	s_add_i32 s10, s10, s12
	v_cvt_pk_bf16_f32 v16, v10, v11
	v_add_u32_e32 v14, s10, v3
	v_lshlrev_b32_e32 v18, 16, v50
	v_and_b32_e32 v19, 0xffff0000, v50
	global_store_dword v14, v16, s[8:9]
	v_pk_fma_f32 v[10:11], v[10:11], v[112:113], v[18:19]
	s_add_i32 s10, s10, s12
	v_cvt_pk_bf16_f32 v17, v10, v11
	v_add_u32_e32 v14, s10, v3
	v_lshlrev_b32_e32 v18, 16, v51
	v_and_b32_e32 v19, 0xffff0000, v51
	global_store_dword v14, v17, s[8:9]
	v_pk_fma_f32 v[10:11], v[10:11], v[114:115], v[18:19]
	s_add_i32 s10, s10, s12
	v_add_u32_e32 v12, s88, v12
	s_mov_b32 s10, 0x1ffff
	v_cmp_lt_i32_e32 vcc, s10, v12
	s_or_b64 s[4:5], vcc, s[4:5]
	s_andn2_b64 exec, exec, s[4:5]
	s_cbranch_execnz .LBB0_150
